# final RMSNorm row loop: both 16-byte loads of a row issued together (was load, wait, unpack, load, wait)
# baseline (speedup 1.0000x reference)
.LBB0_1443:
	global_load_dwordx4 v[30:33], v[20:21], off offset:-1024
	global_load_dwordx4 v[204:207], v[20:21], off
	v_add_u32_e32 v18, s2, v18
	s_waitcnt vmcnt(1)
	v_lshlrev_b32_e32 v34, 16, v30
	v_and_b32_e32 v35, 0xffff0000, v30
	v_lshlrev_b32_e32 v36, 16, v31
	v_and_b32_e32 v37, 0xffff0000, v31
	v_lshlrev_b32_e32 v38, 16, v32
	v_and_b32_e32 v39, 0xffff0000, v32
	v_lshlrev_b32_e32 v40, 16, v33
	v_and_b32_e32 v41, 0xffff0000, v33
	v_mul_f32_e32 v0, v35, v35
	v_fmac_f32_e32 v0, v34, v34
	v_fmac_f32_e32 v0, v36, v36
	v_fmac_f32_e32 v0, v37, v37
	v_fmac_f32_e32 v0, v38, v38
	v_fmac_f32_e32 v0, v39, v39
	v_fmac_f32_e32 v0, v40, v40
	v_fmac_f32_e32 v0, v41, v41
	v_lshl_add_u64 v[20:21], v[20:21], 0, s[46:47]
	s_waitcnt vmcnt(0)
	v_lshlrev_b32_e32 v42, 16, v204
	v_and_b32_e32 v43, 0xffff0000, v204
	v_fmac_f32_e32 v0, v42, v42
	v_lshlrev_b32_e32 v44, 16, v205
	v_fmac_f32_e32 v0, v43, v43
	v_and_b32_e32 v46, 0xffff0000, v206
	v_and_b32_e32 v45, 0xffff0000, v205
	v_fmac_f32_e32 v0, v44, v44
	v_lshlrev_b32_e32 v49, 16, v206
	v_mov_b32_e32 v48, v46
	v_fmac_f32_e32 v0, v45, v45
	v_pk_mul_f32 v[30:31], v[48:49], v[48:49]
	v_lshlrev_b32_e32 v51, 16, v207
	v_add_f32_e32 v0, v31, v0
	v_add_f32_e32 v19, v30, v0
	v_and_b32_e32 v0, 0xffff0000, v207
	v_mov_b32_e32 v50, v0
	v_pk_mul_f32 v[30:31], v[50:51], v[50:51]
	v_and_b32_e32 v47, s0, v207
	v_add_f32_e32 v19, v31, v19
	v_add_f32_e32 v19, v30, v19
	ds_bpermute_b32 v30, v24, v19
	s_waitcnt lgkmcnt(0)
	v_add_f32_e32 v19, v19, v30
	ds_bpermute_b32 v30, v25, v19
	s_waitcnt lgkmcnt(0)
	v_add_f32_e32 v19, v19, v30
	ds_bpermute_b32 v30, v26, v19
	s_waitcnt lgkmcnt(0)
	v_add_f32_e32 v19, v19, v30
	ds_bpermute_b32 v30, v27, v19
	s_waitcnt lgkmcnt(0)
	v_add_f32_e32 v19, v19, v30
	ds_bpermute_b32 v30, v28, v19
	s_waitcnt lgkmcnt(0)
	v_add_f32_e32 v19, v19, v30
	ds_bpermute_b32 v30, v29, v19
	s_waitcnt lgkmcnt(0)
	v_add_f32_e32 v19, v19, v30
	v_fmamk_f32 v19, v19, 0x3a800000, v194
	v_cmp_gt_f32_e32 vcc, s76, v19
	v_mul_f32_e32 v30, 0x4b800000, v19
	s_nop 0
	v_cndmask_b32_e32 v19, v19, v30, vcc
	v_rsq_f32_e32 v19, v19
	s_nop 0
	v_mul_f32_e32 v30, 0x45800000, v19
	v_cndmask_b32_e32 v52, v19, v30, vcc
	v_pk_mul_f32 v[30:31], v[34:35], v[52:53] op_sel_hi:[1,0]
	v_pk_mul_f32 v[32:33], v[36:37], v[52:53] op_sel_hi:[1,0]
	v_pk_mul_f32 v[34:35], v[38:39], v[52:53] op_sel_hi:[1,0]
	v_pk_mul_f32 v[36:37], v[40:41], v[52:53] op_sel_hi:[1,0]
	v_pk_mul_f32 v[32:33], v[8:9], v[32:33]
	v_pk_mul_f32 v[30:31], v[6:7], v[30:31]
	v_pk_mul_f32 v[36:37], v[4:5], v[36:37]
	v_pk_mul_f32 v[34:35], v[2:3], v[34:35]
	global_store_dwordx4 v[22:23], v[30:33], off
	global_store_dwordx4 v[22:23], v[34:37], off offset:16
	v_cmp_lt_i32_e32 vcc, s8, v18
	v_pk_mul_f32 v[30:31], v[42:43], v[52:53] op_sel_hi:[1,0]
	v_pk_mul_f32 v[32:33], v[44:45], v[52:53] op_sel_hi:[1,0]
	v_pk_mov_b32 v[34:35], v[48:49], v[46:47] op_sel:[1,0]
	v_pk_mov_b32 v[36:37], v[50:51], v[0:1] op_sel:[1,0]
	v_pk_mul_f32 v[32:33], v[16:17], v[32:33]
	v_pk_mul_f32 v[30:31], v[14:15], v[30:31]
	v_pk_mul_f32 v[34:35], v[52:53], v[34:35] op_sel_hi:[0,1]
	v_pk_mul_f32 v[36:37], v[52:53], v[36:37] op_sel_hi:[0,1]
	v_pk_mul_f32 v[36:37], v[12:13], v[36:37]
	v_pk_mul_f32 v[34:35], v[10:11], v[34:35]
	global_store_dwordx4 v[22:23], v[30:33], off offset:2048
	global_store_dwordx4 v[22:23], v[34:37], off offset:2064
	v_lshl_add_u64 v[22:23], v[22:23], 0, s[12:13]
	s_or_b64 s[6:7], vcc, s[6:7]
	s_andn2_b64 exec, exec, s[6:7]
	s_cbranch_execnz .LBB0_1443
